# v83 + scan publisher-wave partial-sum reads batched (all six reduce sites now issue their four LDS reads together)
# speedup vs baseline: 1.0023x; 1.0023x over previous
.LBB0_461:
	v_lshl_add_u64 v[188:189], s[60:61], 0, v[170:171]
	s_mov_b32 s33, 0xe781000
	v_add_co_u32_e32 v84, vcc, s33, v188
	v_lshl_add_u64 v[200:201], s[60:61], 0, v[166:167]
	s_nop 0
	v_addc_co_u32_e32 v85, vcc, 0, v189, vcc
	v_add_co_u32_e32 v86, vcc, s82, v200
	v_lshl_add_u64 v[202:203], s[60:61], 0, v[168:169]
	s_nop 0
	v_addc_co_u32_e32 v87, vcc, 0, v201, vcc
	global_load_dwordx4 v[136:139], v[84:85], off
	global_load_dwordx4 v[124:127], v[86:87], off
	global_load_dwordx4 v[112:115], v[86:87], off offset:1024
	global_load_dwordx4 v[108:111], v[86:87], off offset:2048
	v_add_co_u32_e32 v84, vcc, s83, v200
	s_add_i32 s33, s18, 3
	s_nop 0
	v_addc_co_u32_e32 v85, vcc, 0, v201, vcc
	global_load_dwordx4 v[104:107], v[86:87], off offset:3072
	global_load_dwordx4 v[100:103], v[84:85], off
	global_load_dwordx4 v[92:95], v[84:85], off offset:1024
	global_load_dwordx4 v[96:99], v[84:85], off offset:2048
	global_load_dwordx4 v[88:91], v[84:85], off offset:3072
	global_load_dwordx4 v[120:123], v[202:203], off offset:-1024
	global_load_dwordx4 v[116:119], v[202:203], off offset:-960
	s_and_b32 s54, s33, 1
	s_lshl_b32 s55, s54, 15
	s_lshl_b32 s54, s54, 11
	s_add_i32 s54, s69, s54
	v_add_u32_e32 v204, s54, v163
	ds_read_b64_tr_b16 v[84:85], v204
	v_add_u32_e32 v205, 0x80, v204
	ds_read_b64_tr_b16 v[86:87], v205
	v_add_u32_e32 v206, 0x400, v204
	ds_read_b64_tr_b16 v[184:185], v206
	v_add_u32_e32 v207, 0x480, v204
	ds_read_b64_tr_b16 v[186:187], v207
	s_waitcnt lgkmcnt(0)
	s_add_i32 s54, s55, 0
	v_cvt_pk_bf16_f32 v180, v128, v129
	v_cvt_pk_bf16_f32 v181, v130, v131
	v_cvt_pk_bf16_f32 v182, v132, v133
	v_cvt_pk_bf16_f32 v183, v134, v135
	v_lshlrev_b32_e32 v208, 2, v149
	s_waitcnt vmcnt(31)
	v_mfma_f32_16x16x32_bf16 v[12:15], v[12:15], v[180:183], 0
	s_add_i32 s55, s68, s54
	s_waitcnt vmcnt(22)
	v_pk_mul_f32 v[34:35], v[134:135], v[34:35]
	v_pk_mul_f32 v[32:33], v[132:133], v[32:33]
	v_mfma_f32_16x16x32_bf16 v[8:11], v[8:11], v[180:183], 0
	v_lshlrev_b32_e32 v209, 2, v190
	v_pk_mul_f32 v[42:43], v[130:131], v[42:43]
	v_pk_mul_f32 v[40:41], v[128:129], v[40:41]
	v_mfma_f32_16x16x32_bf16 v[4:7], v[4:7], v[180:183], 0
	s_add_i32 s18, s18, 4
	s_and_b32 s18, s18, 1
	v_mfma_f32_16x16x32_bf16 v[0:3], v[0:3], v[180:183], 0
	v_add_u32_e32 v182, s55, v208
	s_add_i32 s55, s66, 0xfffff800
	s_andn2_b32 s55, 0x800, s55
	s_add_i32 s55, s71, s55
	ds_write2st64_b32 v182, v12, v13 offset1:1
	ds_write2st64_b32 v182, v14, v15 offset0:2 offset1:3
	ds_write2st64_b32 v182, v8, v9 offset0:4 offset1:5
	ds_write2st64_b32 v182, v10, v11 offset0:6 offset1:7
	ds_write2st64_b32 v182, v4, v5 offset0:8 offset1:9
	ds_write2st64_b32 v182, v6, v7 offset0:10 offset1:11
	ds_write2st64_b32 v182, v0, v1 offset0:12 offset1:13
	ds_write2st64_b32 v182, v2, v3 offset0:14 offset1:15
	v_mfma_f32_16x16x32_bf16 v[0:3], v[20:23], v[84:87], v[32:35]
	v_add_u32_e32 v4, s55, v140
	v_add_u32_e32 v4, 0xffffe800, v4
	v_add_u32_e32 v183, s54, v209
	s_waitcnt vmcnt(21)
	ds_write_b128 v4, v[80:83]
	s_waitcnt lgkmcnt(0)
	s_barrier
	ds_read2st64_b64 v[4:7], v183 offset1:8
	ds_read2st64_b64 v[228:231], v183 offset0:16 offset1:24
	ds_read2st64_b64 v[220:223], v183 offset0:32 offset1:40
	ds_read2st64_b64 v[224:227], v183 offset0:48 offset1:56
	v_mfma_f32_16x16x32_bf16 v[80:83], v[16:19], v[184:187], v[0:3]
	v_lshl_add_u64 v[180:181], s[60:61], 0, v[164:165]
	s_mov_b32 s54, 0xe841000
	s_waitcnt lgkmcnt(3)
	v_add_f32_e32 v4, 0, v4
	v_add_f32_e32 v5, 0, v5
	v_add_f32_e32 v4, v4, v6
	v_add_f32_e32 v8, v5, v7
	v_mfma_f32_16x16x32_bf16 v[12:15], v[24:27], v[84:87], v[40:43]
	s_waitcnt lgkmcnt(2)
	v_add_f32_e32 v0, v4, v228
	v_add_f32_e32 v1, v8, v229
	v_add_f32_e32 v8, v0, v230
	v_add_f32_e32 v9, v1, v231
	s_waitcnt lgkmcnt(1)
	v_add_f32_e32 v4, v8, v220
	v_add_f32_e32 v5, v9, v221
	v_add_f32_e32 v4, v4, v222
	v_add_f32_e32 v5, v5, v223
	s_waitcnt lgkmcnt(0)
	v_add_f32_e32 v0, v4, v224
	v_add_f32_e32 v1, v5, v225
	v_add_f32_e32 v0, v0, v226
	v_add_f32_e32 v1, v1, v227
	v_cvt_pk_bf16_f32 v2, v0, v1
	v_add_co_u32_e32 v0, vcc, s84, v180
	v_mfma_f32_16x16x32_bf16 v[128:131], v[28:31], v[184:187], v[12:15]
	s_nop 0
	v_addc_co_u32_e32 v1, vcc, 0, v181, vcc
	global_store_dword v[0:1], v2, off
	v_add_co_u32_e32 v0, vcc, s54, v188
	s_lshl_b32 s54, s18, 15
	s_nop 0
	v_addc_co_u32_e32 v1, vcc, 0, v189, vcc
	v_add_co_u32_e32 v2, vcc, s85, v200
	s_lshl_b32 s18, s18, 11
	s_nop 0
	v_addc_co_u32_e32 v3, vcc, 0, v201, vcc
	v_add_co_u32_e32 v16, vcc, s86, v200
	global_load_dwordx4 v[84:87], v[0:1], off
	global_load_dwordx4 v[12:15], v[2:3], off
	global_load_dwordx4 v[8:11], v[2:3], off offset:1024
	global_load_dwordx4 v[4:7], v[2:3], off offset:2048
	v_addc_co_u32_e32 v17, vcc, 0, v201, vcc
	global_load_dwordx4 v[0:3], v[2:3], off offset:3072
	s_nop 0
	global_load_dwordx4 v[24:27], v[16:17], off
	global_load_dwordx4 v[28:31], v[16:17], off offset:1024
	global_load_dwordx4 v[20:23], v[16:17], off offset:2048
	s_nop 0
	global_load_dwordx4 v[16:19], v[16:17], off offset:3072
	s_nop 0
	global_load_dwordx4 v[40:43], v[202:203], off
	global_load_dwordx4 v[32:35], v[202:203], off offset:64
	s_add_i32 s18, s69, s18
	v_add_u32_e32 v186, s18, v163
	ds_read_b64_tr_b16 v[132:133], v186
	v_add_u32_e32 v134, 0x80, v186
	ds_read_b64_tr_b16 v[134:135], v134
	v_add_u32_e32 v184, 0x400, v186
	ds_read_b64_tr_b16 v[184:185], v184
	v_add_u32_e32 v186, 0x480, v186
	ds_read_b64_tr_b16 v[186:187], v186
	s_waitcnt lgkmcnt(0)
	s_waitcnt vmcnt(24)
	v_pk_mul_f32 v[78:79], v[78:79], v[130:131]
	v_pk_mul_f32 v[76:77], v[76:77], v[128:129]
	v_cvt_pk_bf16_f32 v200, v128, v129
	v_cvt_pk_bf16_f32 v201, v130, v131
	v_cvt_pk_bf16_f32 v202, v80, v81
	v_cvt_pk_bf16_f32 v203, v82, v83
	s_add_i32 s18, s54, 0
	v_mfma_f32_16x16x32_bf16 v[64:67], v[64:67], v[200:203], 0
	s_add_i32 s54, s68, s18
	s_waitcnt vmcnt(23)
	v_pk_mul_f32 v[72:73], v[72:73], v[80:81]
	v_add_u32_e32 v80, s54, v208
	v_mfma_f32_16x16x32_bf16 v[68:71], v[68:71], v[200:203], 0
	s_andn2_b32 s54, 0x800, s66
	v_pk_mul_f32 v[74:75], v[74:75], v[82:83]
	s_add_i32 s54, s71, s54
	v_mfma_f32_16x16x32_bf16 v[36:39], v[36:39], v[200:203], 0
	ds_write2st64_b32 v80, v64, v65 offset1:1
	ds_write2st64_b32 v80, v66, v67 offset0:2 offset1:3
	s_nop 1
	ds_write2st64_b32 v80, v68, v69 offset0:4 offset1:5
	v_mfma_f32_16x16x32_bf16 v[44:47], v[44:47], v[132:135], v[76:79]
	v_mfma_f32_16x16x32_bf16 v[56:59], v[56:59], v[200:203], 0
	ds_write2st64_b32 v80, v70, v71 offset0:6 offset1:7
	s_nop 6
	ds_write2st64_b32 v80, v56, v57 offset0:8 offset1:9
	ds_write2st64_b32 v80, v58, v59 offset0:10 offset1:11
	v_mfma_f32_16x16x32_bf16 v[200:203], v[60:63], v[184:187], v[44:47]
	ds_write2st64_b32 v80, v36, v37 offset0:12 offset1:13
	ds_write2st64_b32 v80, v38, v39 offset0:14 offset1:15
	s_nop 0
	v_add_u32_e32 v44, s54, v140
	v_mfma_f32_16x16x32_bf16 v[36:39], v[48:51], v[132:135], v[72:75]
	v_add_u32_e32 v44, 0xffffe800, v44
	v_add_u32_e32 v48, s18, v209
	s_waitcnt vmcnt(22)
	ds_write_b128 v44, v[136:139]
	s_waitcnt lgkmcnt(0)
	s_barrier
	ds_read2st64_b64 v[44:47], v48 offset1:8
	v_mfma_f32_16x16x32_bf16 v[136:139], v[52:55], v[184:187], v[36:39]
	s_min_u32 s18, s33, 59
	s_add_i32 s54, s18, 4
	s_mul_i32 s18, s54, 0xc0000
	ds_read2st64_b64 v[36:39], v48 offset0:16 offset1:24
	ds_read2st64_b64 v[220:223], v48 offset0:32 offset1:40
	ds_read2st64_b64 v[224:227], v48 offset0:48 offset1:56
	s_waitcnt lgkmcnt(3)
	v_add_f32_e32 v44, 0, v44
	v_add_f32_e32 v45, 0, v45
	v_add_f32_e32 v44, v44, v46
	v_add_f32_e32 v49, v45, v47
	s_waitcnt lgkmcnt(2)
	v_add_f32_e32 v36, v44, v36
	v_add_f32_e32 v37, v49, v37
	v_add_f32_e32 v49, v36, v38
	v_add_f32_e32 v50, v37, v39
	s_waitcnt lgkmcnt(1)
	v_add_f32_e32 v44, v49, v220
	v_add_f32_e32 v45, v50, v221
	v_add_f32_e32 v44, v44, v222
	v_add_f32_e32 v45, v45, v223
	s_waitcnt lgkmcnt(0)
	v_add_f32_e32 v36, v44, v224
	v_add_f32_e32 v37, v45, v225
	v_add_f32_e32 v36, v36, v226
	v_add_f32_e32 v37, v37, v227
	v_cvt_pk_bf16_f32 v38, v36, v37
	v_add_co_u32_e32 v36, vcc, s87, v180
	s_nop 1
	v_addc_co_u32_e32 v37, vcc, 0, v181, vcc
	global_store_dword v[36:37], v38, off
	v_lshl_add_u64 v[36:37], v[172:173], 0, s[18:19]
	s_lshl_b32 s18, s54, 15
	v_lshl_add_u64 v[38:39], v[174:175], 0, s[18:19]
	v_lshl_add_u64 v[52:53], v[176:177], 0, s[18:19]
	s_lshl_b32 s18, s54, 10
	global_load_dwordx4 v[80:83], v[36:37], off
	global_load_dwordx4 v[64:67], v[38:39], off
	global_load_dwordx4 v[68:71], v[38:39], off offset:1024
	global_load_dwordx4 v[56:59], v[38:39], off offset:2048
	s_nop 0
	global_load_dwordx4 v[36:39], v[38:39], off offset:3072
	s_nop 0
	global_load_dwordx4 v[44:47], v[52:53], off
	global_load_dwordx4 v[60:63], v[52:53], off offset:1024
	global_load_dwordx4 v[48:51], v[52:53], off offset:2048
	v_lshl_add_u64 v[72:73], v[178:179], 0, s[18:19]
	global_load_dwordx4 v[52:55], v[52:53], off offset:3072
	s_nop 0
	global_load_dwordx4 v[76:79], v[72:73], off
	s_nop 0
	global_load_dwordx4 v[72:75], v[72:73], off offset:64
	ds_read_b64_tr_b16 v[128:129], v204
	ds_read_b64_tr_b16 v[130:131], v205
	ds_read_b64_tr_b16 v[132:133], v206
	ds_read_b64_tr_b16 v[134:135], v207
	s_waitcnt lgkmcnt(0)
	s_waitcnt vmcnt(25)
	v_pk_mul_f32 v[122:123], v[122:123], v[202:203]
	v_pk_mul_f32 v[120:121], v[120:121], v[200:201]
	v_cvt_pk_bf16_f32 v184, v200, v201
	v_cvt_pk_bf16_f32 v185, v202, v203
	v_cvt_pk_bf16_f32 v186, v136, v137
	v_cvt_pk_bf16_f32 v187, v138, v139
	s_add_i32 s54, s66, 0x800
	v_mfma_f32_16x16x32_bf16 v[124:127], v[124:127], v[184:187], 0
	s_andn2_b32 s54, 0x800, s54
	s_waitcnt vmcnt(24)
	v_pk_mul_f32 v[118:119], v[118:119], v[138:139]
	v_pk_mul_f32 v[116:117], v[116:117], v[136:137]
	v_mfma_f32_16x16x32_bf16 v[100:103], v[100:103], v[128:131], v[120:123]
	s_add_i32 s54, s71, s54
	v_add_co_u32_e32 v136, vcc, s88, v180
	v_mfma_f32_16x16x32_bf16 v[112:115], v[112:115], v[184:187], 0
	s_addk_i32 s66, 0x1800
	v_addc_co_u32_e32 v137, vcc, 0, v181, vcc
	v_mfma_f32_16x16x32_bf16 v[96:99], v[96:99], v[128:131], v[116:119]
	v_lshl_add_u64 v[164:165], v[164:165], 0, s[42:43]
	v_lshl_add_u64 v[166:167], v[166:167], 0, s[48:49]
	v_lshl_add_u64 v[168:169], v[168:169], 0, s[50:51]
	v_add_u32_e32 v116, s54, v140
	v_mfma_f32_16x16x32_bf16 v[108:111], v[108:111], v[184:187], 0
	v_add_u32_e32 v116, 0xffffe800, v116
	v_lshl_add_u64 v[170:171], v[170:171], 0, s[58:59]
	s_mov_b32 s18, s33
	v_mfma_f32_16x16x32_bf16 v[104:107], v[104:107], v[184:187], 0
	ds_write2st64_b32 v182, v124, v125 offset1:1
	ds_write2st64_b32 v182, v126, v127 offset0:2 offset1:3
	ds_write2st64_b32 v182, v112, v113 offset0:4 offset1:5
	ds_write2st64_b32 v182, v114, v115 offset0:6 offset1:7
	ds_write2st64_b32 v182, v108, v109 offset0:8 offset1:9
	ds_write2st64_b32 v182, v110, v111 offset0:10 offset1:11
	s_nop 1
	ds_write2st64_b32 v182, v104, v105 offset0:12 offset1:13
	ds_write2st64_b32 v182, v106, v107 offset0:14 offset1:15
	s_waitcnt vmcnt(22)
	ds_write_b128 v116, v[84:87]
	s_waitcnt lgkmcnt(0)
	s_barrier
	v_mfma_f32_16x16x32_bf16 v[128:131], v[92:95], v[132:135], v[100:103]
	ds_read2st64_b64 v[92:95], v183 offset1:8
	s_cmp_lt_u32 s33, 60
	v_mfma_f32_16x16x32_bf16 v[132:135], v[88:91], v[132:135], v[96:99]
	ds_read2st64_b64 v[88:91], v183 offset0:16 offset1:24
	s_nop 1
	ds_read2st64_b64 v[96:99], v183 offset0:32 offset1:40
	ds_read2st64_b64 v[100:103], v183 offset0:48 offset1:56
	s_waitcnt lgkmcnt(3)
	v_add_f32_e32 v92, 0, v92
	v_add_f32_e32 v93, 0, v93
	v_add_f32_e32 v92, v92, v94
	v_add_f32_e32 v93, v93, v95
	s_waitcnt lgkmcnt(2)
	v_add_f32_e32 v88, v92, v88
	v_add_f32_e32 v89, v93, v89
	v_add_f32_e32 v88, v88, v90
	v_add_f32_e32 v89, v89, v91
	s_waitcnt lgkmcnt(1)
	v_add_f32_e32 v88, v88, v96
	v_add_f32_e32 v89, v89, v97
	v_add_f32_e32 v88, v88, v98
	v_add_f32_e32 v89, v89, v99
	s_waitcnt lgkmcnt(0)
	v_add_f32_e32 v88, v88, v100
	v_add_f32_e32 v89, v89, v101
	v_add_f32_e32 v88, v88, v102
	v_add_f32_e32 v89, v89, v103
	v_cvt_pk_bf16_f32 v88, v88, v89
	global_store_dword v[136:137], v88, off
	s_cbranch_scc1 .LBB0_461
	s_waitcnt vmcnt(15)
	ds_read_b64_tr_b16 v[16:17], v191
	s_lshl_b32 s18, s64, 12
	ds_read_b64_tr_b16 v[16:17], v193
	s_add_u32 s18, s60, s18
	ds_read_b64_tr_b16 v[16:17], v194
	s_addc_u32 s33, s61, 0
	s_lshl_b32 s54, s65, 1
	ds_read_b64_tr_b16 v[16:17], v195
	s_add_u32 s18, s18, s54
	s_waitcnt lgkmcnt(0)
	s_addc_u32 s33, s33, 0
	s_lshl_b64 s[54:55], s[62:63], 1
	s_add_u32 s54, s18, s54
	s_addc_u32 s55, s33, s55
	v_cvt_pk_bf16_f32 v16, v128, v129
	v_cvt_pk_bf16_f32 v17, v130, v131
	v_cvt_pk_bf16_f32 v18, v132, v133
	v_cvt_pk_bf16_f32 v19, v134, v135
	v_add_u32_e32 v20, s68, v196
	v_mfma_f32_16x16x32_bf16 v[12:15], v[12:15], v[16:19], 0
	v_mfma_f32_16x16x32_bf16 v[8:11], v[8:11], v[16:19], 0
	s_nop 6
	ds_write2st64_b32 v20, v12, v13 offset0:128 offset1:129
	ds_write2st64_b32 v20, v14, v15 offset0:130 offset1:131
	ds_write2st64_b32 v20, v8, v9 offset0:132 offset1:133
	v_mfma_f32_16x16x32_bf16 v[0:3], v[0:3], v[16:19], 0
	v_mfma_f32_16x16x32_bf16 v[4:7], v[4:7], v[16:19], 0
	ds_write2st64_b32 v20, v10, v11 offset0:134 offset1:135
	s_nop 6
	ds_write2st64_b32 v20, v4, v5 offset0:136 offset1:137
	ds_write2st64_b32 v20, v6, v7 offset0:138 offset1:139
	ds_write2st64_b32 v20, v0, v1 offset0:140 offset1:141
	ds_write2st64_b32 v20, v2, v3 offset0:142 offset1:143
	v_add_u32_e32 v0, s72, v140
	ds_write_b128 v0, v[84:87]
	s_waitcnt lgkmcnt(0)
	s_barrier
	ds_read2st64_b64 v[0:3], v197 offset0:64 offset1:72
	ds_read2st64_b64 v[4:7], v197 offset0:80 offset1:88
	s_waitcnt lgkmcnt(1)
	v_add_f32_e32 v0, 0, v0
	v_add_f32_e32 v1, 0, v1
	v_add_f32_e32 v0, v0, v2
	v_add_f32_e32 v8, v1, v3
	s_waitcnt lgkmcnt(0)
	v_add_f32_e32 v4, v0, v4
	ds_read2st64_b64 v[0:3], v197 offset0:96 offset1:104
	v_add_f32_e32 v5, v8, v5
	v_add_f32_e32 v8, v4, v6
	v_add_f32_e32 v9, v5, v7
	ds_read2st64_b64 v[4:7], v197 offset0:112 offset1:120
	s_waitcnt lgkmcnt(1)
	v_add_f32_e32 v0, v8, v0
	v_add_f32_e32 v1, v9, v1
	v_add_f32_e32 v0, v0, v2
	v_add_f32_e32 v1, v1, v3
	s_waitcnt lgkmcnt(0)
	v_add_f32_e32 v0, v0, v4
	v_add_f32_e32 v1, v1, v5
	v_add_f32_e32 v0, v0, v6
	v_add_f32_e32 v1, v1, v7
	v_cvt_pk_bf16_f32 v4, v0, v1
	v_lshl_add_u64 v[0:1], s[54:55], 0, v[146:147]
	v_lshlrev_b32_e32 v2, 1, v148
	v_mov_b32_e32 v3, v143
	v_lshl_add_u64 v[0:1], v[0:1], 0, v[2:3]
	v_add_co_u32_e32 v0, vcc, 0x1a7c0000, v0
	s_nop 1
	v_addc_co_u32_e32 v1, vcc, 0, v1, vcc
	global_store_dword v[0:1], v4, off
	s_barrier
	s_branch .LBB0_454
